# lever 2 (epilogue de-serialisation) on the decode item's final cross-wave reduction: eight ds_read_b128 issued together, added in the same order under counted lgkmcnt
# speedup vs baseline: 1.0183x; 1.0072x over previous
; #define LDS_WAIT() asm volatile("s_waitcnt lgkmcnt(0)" ::: "memory")
; #define DEC_LOADV(dst, i0) do { asm volatile("" ::: "memory"); _Pragma("unroll") for (int u = 0; u < 4; ++u) { const float* vr = cv + rbase + (size_t)((i0) + u) * 512; dst[u][0] = __builtin_nontemporal_load((const f32x4*)(vr + 4 * lane)); dst[u][1] = __builtin_nontemporal_load((const f32x4*)(vr + 256 + 4 * lane)); } } while (0)
; __device__ __forceinline__ void decode_item(Frame& F, const Args& a, int l, int item, unsigned char* ws) {
;     ...
;     LDS_WAIT(); __syncthreads();
;     f32x4 O[4][2];
; #pragma unroll
;     for (int qi = 0; qi < 4; ++qi) { O[qi][0] = (f32x4){0.f, 0.f, 0.f, 0.f}; O[qi][1] = O[qi][0]; }
;     const int hh = lane >> 5;
;     {
;         f32x4 va[4][2], vb[4][2];
;     ...
;         DEC_LOADV(va, 0); DEC_LOADV(vb, 4); DEC_ACC(va, 0); DEC_LOADV(va, 8); DEC_ACC(vb, 4); DEC_LOADV(vb, 12); DEC_ACC(va, 8); DEC_LOADV(va, 16); DEC_ACC(vb, 12); DEC_LOADV(vb, 20); DEC_ACC(va, 16); DEC_LOADV(va, 24); DEC_ACC(vb, 20); DEC_LOADV(vb, 28); DEC_ACC(va, 24); DEC_ACC(vb, 28);
.LBB0_1221:
	s_or_b64 exec, exec, s[0:1]
	v_readlane_b32 s36, v252, 21
	v_readlane_b32 s42, v252, 27
	v_readlane_b32 s43, v252, 28
	s_add_u32 s0, s42, s6
	s_addc_u32 s1, s43, s7
	v_lshl_add_u64 v[2:3], v[118:119], 2, s[0:1]
	s_waitcnt lgkmcnt(0)
	s_waitcnt lgkmcnt(0)
	s_barrier
	v_lshl_add_u64 v[86:87], v[116:117], 2, v[2:3]
	global_load_dwordx4 v[60:63], v[86:87], off nt
	global_load_dwordx4 v[66:69], v[86:87], off offset:1024 nt
	global_load_dwordx4 v[56:59], v[86:87], off offset:2048 nt
	global_load_dwordx4 v[52:55], v[86:87], off offset:3072 nt
	v_add_co_u32_e32 v2, vcc, s69, v86
	s_movk_i32 s0, 0x2000
	s_nop 0
	v_addc_co_u32_e32 v3, vcc, 0, v87, vcc
	v_add_co_u32_e32 v4, vcc, s0, v86
	s_movk_i32 s0, 0x3000
	s_nop 0
	v_addc_co_u32_e32 v5, vcc, 0, v87, vcc
	global_load_dwordx4 v[44:47], v[4:5], off offset:-4096 nt
	global_load_dwordx4 v[48:51], v[2:3], off offset:1024 nt
	global_load_dwordx4 v[40:43], v[2:3], off offset:2048 nt
	global_load_dwordx4 v[36:39], v[2:3], off offset:3072 nt
	global_load_dwordx4 v[30:33], v[4:5], off nt
	global_load_dwordx4 v[26:29], v[4:5], off offset:1024 nt
	global_load_dwordx4 v[22:25], v[4:5], off offset:2048 nt
	global_load_dwordx4 v[18:21], v[4:5], off offset:3072 nt
	v_add_co_u32_e32 v2, vcc, s0, v86
	v_lshlrev_b32_e64 v34, 11, s18
	s_nop 0
	v_addc_co_u32_e32 v3, vcc, 0, v87, vcc
	v_add_co_u32_e32 v64, vcc, s95, v86
	v_and_b32_e32 v70, 0xffffffe0, v122
	s_nop 0
	v_addc_co_u32_e32 v65, vcc, 0, v87, vcc
	global_load_dwordx4 v[14:17], v[64:65], off offset:-4096 nt
	global_load_dwordx4 v[10:13], v[2:3], off offset:1024 nt
	global_load_dwordx4 v[6:9], v[2:3], off offset:2048 nt
	s_nop 0
	global_load_dwordx4 v[2:5], v[2:3], off offset:3072 nt
	v_add3_u32 v34, 0, v34, v70
	ds_read_b128 v[70:73], v34 offset:16384
	ds_read_b128 v[74:77], v34 offset:16400
	s_movk_i32 s0, 0x5000
	v_readlane_b32 s37, v252, 22
	v_readlane_b32 s38, v252, 23
	v_readlane_b32 s39, v252, 24
	v_readlane_b32 s40, v252, 25
	v_readlane_b32 s41, v252, 26
	v_readlane_b32 s44, v252, 29
	v_readlane_b32 s45, v252, 30
	v_readlane_b32 s46, v252, 31
	v_readlane_b32 s47, v252, 32
	v_readlane_b32 s48, v252, 33
	v_readlane_b32 s49, v252, 34
	v_readlane_b32 s50, v252, 35
	v_readlane_b32 s51, v252, 36
	s_waitcnt vmcnt(15) lgkmcnt(1)
	v_pk_fma_f32 v[78:79], v[62:63], v[70:71], 0 op_sel_hi:[1,0,0]
	v_pk_fma_f32 v[80:81], v[60:61], v[70:71], 0 op_sel_hi:[1,0,0]
	s_waitcnt vmcnt(14)
	v_pk_fma_f32 v[82:83], v[68:69], v[70:71], 0 op_sel:[0,1,0] op_sel_hi:[1,1,0]
	v_pk_fma_f32 v[88:89], v[66:67], v[70:71], 0 op_sel:[0,1,0] op_sel_hi:[1,1,0]
	v_pk_fma_f32 v[92:93], v[60:61], v[72:73], 0 op_sel_hi:[1,0,0]
	v_mov_b32_e32 v70, v73
	s_waitcnt lgkmcnt(0)
	v_pk_fma_f32 v[98:99], v[60:61], v[74:75], 0 op_sel_hi:[1,0,0]
	v_pk_fma_f32 v[104:105], v[60:61], v[76:77], 0 op_sel_hi:[1,0,0]
	v_mov_b32_e32 v60, v77
	v_pk_fma_f32 v[90:91], v[62:63], v[72:73], 0 op_sel_hi:[1,0,0]
	v_pk_fma_f32 v[72:73], v[68:69], v[70:71], 0 op_sel_hi:[1,0,0]
	v_pk_fma_f32 v[94:95], v[66:67], v[70:71], 0 op_sel_hi:[1,0,0]
	v_pk_fma_f32 v[96:97], v[62:63], v[74:75], 0 op_sel_hi:[1,0,0]
	v_pk_fma_f32 v[100:101], v[68:69], v[74:75], 0 op_sel:[0,1,0] op_sel_hi:[1,1,0]
	v_pk_fma_f32 v[102:103], v[62:63], v[76:77], 0 op_sel_hi:[1,0,0]
	v_pk_fma_f32 v[76:77], v[68:69], v[60:61], 0 op_sel_hi:[1,0,0]
	v_pk_fma_f32 v[106:107], v[66:67], v[60:61], 0 op_sel_hi:[1,0,0]
	ds_read_b128 v[60:63], v34 offset:16448
	ds_read_b128 v[68:71], v34 offset:16464
	v_pk_fma_f32 v[74:75], v[66:67], v[74:75], 0 op_sel:[0,1,0] op_sel_hi:[1,1,0]
	s_waitcnt vmcnt(13) lgkmcnt(1)
	v_pk_fma_f32 v[92:93], v[56:57], v[62:63], v[92:93] op_sel_hi:[1,0,1]
	v_pk_fma_f32 v[90:91], v[58:59], v[62:63], v[90:91] op_sel_hi:[1,0,1]
	v_mov_b32_e32 v62, v63
	v_pk_fma_f32 v[80:81], v[56:57], v[60:61], v[80:81] op_sel_hi:[1,0,1]
	v_pk_fma_f32 v[78:79], v[58:59], v[60:61], v[78:79] op_sel_hi:[1,0,1]
	s_waitcnt vmcnt(12)
	v_pk_fma_f32 v[88:89], v[52:53], v[60:61], v[88:89] op_sel:[0,1,0]
	v_pk_fma_f32 v[82:83], v[54:55], v[60:61], v[82:83] op_sel:[0,1,0]
	v_pk_fma_f32 v[60:61], v[52:53], v[62:63], v[94:95] op_sel_hi:[1,0,1]
	v_pk_fma_f32 v[94:95], v[54:55], v[62:63], v[72:73] op_sel_hi:[1,0,1]
	s_waitcnt lgkmcnt(0)
	v_pk_fma_f32 v[62:63], v[56:57], v[68:69], v[98:99] op_sel_hi:[1,0,1]
	v_pk_fma_f32 v[96:97], v[58:59], v[68:69], v[96:97] op_sel_hi:[1,0,1]
	v_pk_fma_f32 v[66:67], v[52:53], v[68:69], v[74:75] op_sel:[0,1,0]
	v_pk_fma_f32 v[98:99], v[54:55], v[68:69], v[100:101] op_sel:[0,1,0]
	v_mov_b32_e32 v68, v71
	v_pk_fma_f32 v[56:57], v[56:57], v[70:71], v[104:105] op_sel_hi:[1,0,1]
	v_pk_fma_f32 v[58:59], v[58:59], v[70:71], v[102:103] op_sel_hi:[1,0,1]
	v_pk_fma_f32 v[52:53], v[52:53], v[68:69], v[106:107] op_sel_hi:[1,0,1]
	v_pk_fma_f32 v[54:55], v[54:55], v[68:69], v[76:77] op_sel_hi:[1,0,1]
	ds_read_b128 v[68:71], v34 offset:16512
	ds_read_b128 v[72:75], v34 offset:16528
	s_waitcnt vmcnt(11) lgkmcnt(1)
	v_pk_fma_f32 v[76:77], v[46:47], v[68:69], v[78:79] op_sel_hi:[1,0,1]
	v_pk_fma_f32 v[78:79], v[44:45], v[68:69], v[80:81] op_sel_hi:[1,0,1]
	s_waitcnt vmcnt(10)
	v_pk_fma_f32 v[80:81], v[50:51], v[68:69], v[82:83] op_sel:[0,1,0]
	v_pk_fma_f32 v[68:69], v[48:49], v[68:69], v[88:89] op_sel:[0,1,0]
	v_pk_fma_f32 v[82:83], v[46:47], v[70:71], v[90:91] op_sel_hi:[1,0,1]
	v_pk_fma_f32 v[88:89], v[44:45], v[70:71], v[92:93] op_sel_hi:[1,0,1]
	v_mov_b32_e32 v70, v71
	s_waitcnt lgkmcnt(0)
; #define DEC_LOADV(dst, i0) do { asm volatile("" ::: "memory"); _Pragma("unroll") for (int u = 0; u < 4; ++u) { const float* vr = cv + rbase + (size_t)((i0) + u) * 512; dst[u][0] = __builtin_nontemporal_load((const f32x4*)(vr + 4 * lane)); dst[u][1] = __builtin_nontemporal_load((const f32x4*)(vr + 256 + 4 * lane)); } } while (0)
; __device__ __forceinline__ void decode_item(Frame& F, const Args& a, int l, int item, unsigned char* ws) {
;     ...
;         DEC_LOADV(va, 0); DEC_LOADV(vb, 4); DEC_ACC(va, 0); DEC_LOADV(va, 8); DEC_ACC(vb, 4); DEC_LOADV(vb, 12); DEC_ACC(va, 8); DEC_LOADV(va, 16); DEC_ACC(vb, 12); DEC_LOADV(vb, 20); DEC_ACC(va, 16); DEC_LOADV(va, 24); DEC_ACC(vb, 20); DEC_LOADV(vb, 28); DEC_ACC(va, 24); DEC_ACC(vb, 28);
	v_pk_fma_f32 v[62:63], v[44:45], v[72:73], v[62:63] op_sel_hi:[1,0,1]
	v_pk_fma_f32 v[56:57], v[44:45], v[74:75], v[56:57] op_sel_hi:[1,0,1]
	v_mov_b32_e32 v44, v75
	v_pk_fma_f32 v[90:91], v[50:51], v[70:71], v[94:95] op_sel_hi:[1,0,1]
	v_pk_fma_f32 v[60:61], v[48:49], v[70:71], v[60:61] op_sel_hi:[1,0,1]
	v_pk_fma_f32 v[70:71], v[46:47], v[72:73], v[96:97] op_sel_hi:[1,0,1]
	v_pk_fma_f32 v[92:93], v[50:51], v[72:73], v[98:99] op_sel:[0,1,0]
	v_pk_fma_f32 v[66:67], v[48:49], v[72:73], v[66:67] op_sel:[0,1,0]
	v_pk_fma_f32 v[58:59], v[46:47], v[74:75], v[58:59] op_sel_hi:[1,0,1]
	v_pk_fma_f32 v[54:55], v[50:51], v[44:45], v[54:55] op_sel_hi:[1,0,1]
	v_pk_fma_f32 v[52:53], v[48:49], v[44:45], v[52:53] op_sel_hi:[1,0,1]
	ds_read_b128 v[44:47], v34 offset:16576
	ds_read_b128 v[48:51], v34 offset:16592
	s_waitcnt vmcnt(9) lgkmcnt(1)
	v_pk_fma_f32 v[72:73], v[42:43], v[44:45], v[76:77] op_sel_hi:[1,0,1]
	v_pk_fma_f32 v[74:75], v[40:41], v[44:45], v[78:79] op_sel_hi:[1,0,1]
	s_waitcnt vmcnt(8)
	v_pk_fma_f32 v[80:81], v[38:39], v[44:45], v[80:81] op_sel:[0,1,0]
	v_pk_fma_f32 v[94:95], v[36:37], v[44:45], v[68:69] op_sel:[0,1,0]
	v_pk_fma_f32 v[88:89], v[40:41], v[46:47], v[88:89] op_sel_hi:[1,0,1]
	v_mov_b32_e32 v44, v47
	s_waitcnt lgkmcnt(0)
	v_pk_fma_f32 v[100:101], v[40:41], v[48:49], v[62:63] op_sel_hi:[1,0,1]
	v_pk_fma_f32 v[106:107], v[40:41], v[50:51], v[56:57] op_sel_hi:[1,0,1]
	v_mov_b32_e32 v40, v51
	v_pk_fma_f32 v[96:97], v[36:37], v[44:45], v[60:61] op_sel_hi:[1,0,1]
	v_pk_fma_f32 v[98:99], v[42:43], v[48:49], v[70:71] op_sel_hi:[1,0,1]
	v_pk_fma_f32 v[108:109], v[38:39], v[40:41], v[54:55] op_sel_hi:[1,0,1]
	v_pk_fma_f32 v[110:111], v[36:37], v[40:41], v[52:53] op_sel_hi:[1,0,1]
	global_load_dwordx4 v[68:71], v[64:65], off nt
	global_load_dwordx4 v[76:79], v[64:65], off offset:1024 nt
	global_load_dwordx4 v[60:63], v[64:65], off offset:2048 nt
	global_load_dwordx4 v[52:55], v[64:65], off offset:3072 nt
	v_pk_fma_f32 v[102:103], v[36:37], v[48:49], v[66:67] op_sel:[0,1,0]
	v_add_co_u32_e32 v36, vcc, s0, v86
	s_movk_i32 s0, 0x6000
	s_nop 0
	v_addc_co_u32_e32 v37, vcc, 0, v87, vcc
	v_add_co_u32_e32 v112, vcc, s0, v86
	v_pk_fma_f32 v[82:83], v[42:43], v[46:47], v[82:83] op_sel_hi:[1,0,1]
	s_nop 0
	v_addc_co_u32_e32 v113, vcc, 0, v87, vcc
	v_pk_fma_f32 v[90:91], v[38:39], v[44:45], v[90:91] op_sel_hi:[1,0,1]
	v_pk_fma_f32 v[92:93], v[38:39], v[48:49], v[92:93] op_sel:[0,1,0]
	v_pk_fma_f32 v[104:105], v[42:43], v[50:51], v[58:59] op_sel_hi:[1,0,1]
	global_load_dwordx4 v[48:51], v[112:113], off offset:-4096 nt
	global_load_dwordx4 v[44:47], v[36:37], off offset:1024 nt
	global_load_dwordx4 v[40:43], v[36:37], off offset:2048 nt
	s_nop 0
	global_load_dwordx4 v[36:39], v[36:37], off offset:3072 nt
	ds_read_b128 v[56:59], v34 offset:16640
	ds_read_b128 v[64:67], v34 offset:16656
	s_movk_i32 s0, 0x7000
	s_waitcnt vmcnt(15) lgkmcnt(1)
	v_pk_fma_f32 v[82:83], v[32:33], v[58:59], v[82:83] op_sel_hi:[1,0,1]
	v_pk_fma_f32 v[88:89], v[30:31], v[58:59], v[88:89] op_sel_hi:[1,0,1]
	v_mov_b32_e32 v58, v59
	v_pk_fma_f32 v[74:75], v[30:31], v[56:57], v[74:75] op_sel_hi:[1,0,1]
	s_waitcnt vmcnt(14)
	v_pk_fma_f32 v[90:91], v[28:29], v[58:59], v[90:91] op_sel_hi:[1,0,1]
	v_pk_fma_f32 v[58:59], v[26:27], v[58:59], v[96:97] op_sel_hi:[1,0,1]
	s_waitcnt lgkmcnt(0)
	v_pk_fma_f32 v[96:97], v[30:31], v[64:65], v[100:101] op_sel_hi:[1,0,1]
	v_pk_fma_f32 v[100:101], v[30:31], v[66:67], v[106:107] op_sel_hi:[1,0,1]
	v_mov_b32_e32 v30, v67
	v_pk_fma_f32 v[72:73], v[32:33], v[56:57], v[72:73] op_sel_hi:[1,0,1]
	v_pk_fma_f32 v[80:81], v[28:29], v[56:57], v[80:81] op_sel:[0,1,0]
	v_pk_fma_f32 v[56:57], v[26:27], v[56:57], v[94:95] op_sel:[0,1,0]
	v_pk_fma_f32 v[94:95], v[32:33], v[64:65], v[98:99] op_sel_hi:[1,0,1]
	v_pk_fma_f32 v[92:93], v[28:29], v[64:65], v[92:93] op_sel:[0,1,0]
	v_pk_fma_f32 v[64:65], v[26:27], v[64:65], v[102:103] op_sel:[0,1,0]
	v_pk_fma_f32 v[98:99], v[32:33], v[66:67], v[104:105] op_sel_hi:[1,0,1]
	v_pk_fma_f32 v[66:67], v[28:29], v[30:31], v[108:109] op_sel_hi:[1,0,1]
	v_pk_fma_f32 v[102:103], v[26:27], v[30:31], v[110:111] op_sel_hi:[1,0,1]
	ds_read_b128 v[26:29], v34 offset:16704
	ds_read_b128 v[30:33], v34 offset:16720
	s_waitcnt vmcnt(13) lgkmcnt(1)
	v_pk_fma_f32 v[72:73], v[24:25], v[26:27], v[72:73] op_sel_hi:[1,0,1]
	v_pk_fma_f32 v[74:75], v[22:23], v[26:27], v[74:75] op_sel_hi:[1,0,1]
	s_waitcnt vmcnt(12)
	v_pk_fma_f32 v[80:81], v[20:21], v[26:27], v[80:81] op_sel:[0,1,0]
	v_pk_fma_f32 v[26:27], v[18:19], v[26:27], v[56:57] op_sel:[0,1,0]
	v_pk_fma_f32 v[56:57], v[24:25], v[28:29], v[82:83] op_sel_hi:[1,0,1]
	v_pk_fma_f32 v[82:83], v[22:23], v[28:29], v[88:89] op_sel_hi:[1,0,1]
	v_mov_b32_e32 v28, v29
	v_pk_fma_f32 v[88:89], v[20:21], v[28:29], v[90:91] op_sel_hi:[1,0,1]
	v_pk_fma_f32 v[28:29], v[18:19], v[28:29], v[58:59] op_sel_hi:[1,0,1]
	s_waitcnt lgkmcnt(0)
	v_pk_fma_f32 v[58:59], v[24:25], v[30:31], v[94:95] op_sel_hi:[1,0,1]
	v_pk_fma_f32 v[90:91], v[22:23], v[30:31], v[96:97] op_sel_hi:[1,0,1]
	v_pk_fma_f32 v[94:95], v[22:23], v[32:33], v[100:101] op_sel_hi:[1,0,1]
	v_mov_b32_e32 v22, v33
	v_pk_fma_f32 v[92:93], v[20:21], v[30:31], v[92:93] op_sel:[0,1,0]
	v_pk_fma_f32 v[30:31], v[18:19], v[30:31], v[64:65] op_sel:[0,1,0]
	v_pk_fma_f32 v[64:65], v[24:25], v[32:33], v[98:99] op_sel_hi:[1,0,1]
	v_pk_fma_f32 v[32:33], v[20:21], v[22:23], v[66:67] op_sel_hi:[1,0,1]
	v_pk_fma_f32 v[66:67], v[18:19], v[22:23], v[102:103] op_sel_hi:[1,0,1]
	ds_read_b128 v[18:21], v34 offset:16768
	ds_read_b128 v[22:25], v34 offset:16784
	s_waitcnt vmcnt(11) lgkmcnt(1)
; #define DEC_LOADV(dst, i0) do { asm volatile("" ::: "memory"); _Pragma("unroll") for (int u = 0; u < 4; ++u) { const float* vr = cv + rbase + (size_t)((i0) + u) * 512; dst[u][0] = __builtin_nontemporal_load((const f32x4*)(vr + 4 * lane)); dst[u][1] = __builtin_nontemporal_load((const f32x4*)(vr + 256 + 4 * lane)); } } while (0)
; __device__ __forceinline__ void decode_item(Frame& F, const Args& a, int l, int item, unsigned char* ws) {
;     ...
;         DEC_LOADV(va, 0); DEC_LOADV(vb, 4); DEC_ACC(va, 0); DEC_LOADV(va, 8); DEC_ACC(vb, 4); DEC_LOADV(vb, 12); DEC_ACC(va, 8); DEC_LOADV(va, 16); DEC_ACC(vb, 12); DEC_LOADV(vb, 20); DEC_ACC(va, 16); DEC_LOADV(va, 24); DEC_ACC(vb, 20); DEC_LOADV(vb, 28); DEC_ACC(va, 24); DEC_ACC(vb, 28);
	v_pk_fma_f32 v[72:73], v[16:17], v[18:19], v[72:73] op_sel_hi:[1,0,1]
	v_pk_fma_f32 v[74:75], v[14:15], v[18:19], v[74:75] op_sel_hi:[1,0,1]
	s_waitcnt vmcnt(10)
	v_pk_fma_f32 v[80:81], v[12:13], v[18:19], v[80:81] op_sel:[0,1,0]
	v_pk_fma_f32 v[18:19], v[10:11], v[18:19], v[26:27] op_sel:[0,1,0]
	v_pk_fma_f32 v[26:27], v[16:17], v[20:21], v[56:57] op_sel_hi:[1,0,1]
	v_pk_fma_f32 v[56:57], v[14:15], v[20:21], v[82:83] op_sel_hi:[1,0,1]
	v_mov_b32_e32 v20, v21
	v_pk_fma_f32 v[82:83], v[12:13], v[20:21], v[88:89] op_sel_hi:[1,0,1]
	v_pk_fma_f32 v[20:21], v[10:11], v[20:21], v[28:29] op_sel_hi:[1,0,1]
	s_waitcnt lgkmcnt(0)
	v_pk_fma_f32 v[28:29], v[16:17], v[22:23], v[58:59] op_sel_hi:[1,0,1]
	v_pk_fma_f32 v[58:59], v[14:15], v[22:23], v[90:91] op_sel_hi:[1,0,1]
	v_pk_fma_f32 v[88:89], v[12:13], v[22:23], v[92:93] op_sel:[0,1,0]
	v_pk_fma_f32 v[22:23], v[10:11], v[22:23], v[30:31] op_sel:[0,1,0]
	v_pk_fma_f32 v[30:31], v[16:17], v[24:25], v[64:65] op_sel_hi:[1,0,1]
	v_pk_fma_f32 v[64:65], v[14:15], v[24:25], v[94:95] op_sel_hi:[1,0,1]
	v_mov_b32_e32 v14, v25
	v_pk_fma_f32 v[24:25], v[12:13], v[14:15], v[32:33] op_sel_hi:[1,0,1]
	v_pk_fma_f32 v[32:33], v[10:11], v[14:15], v[66:67] op_sel_hi:[1,0,1]
	ds_read_b128 v[10:13], v34 offset:16832
	ds_read_b128 v[14:17], v34 offset:16848
	s_waitcnt vmcnt(9) lgkmcnt(1)
	v_pk_fma_f32 v[90:91], v[8:9], v[10:11], v[72:73] op_sel_hi:[1,0,1]
	v_pk_fma_f32 v[92:93], v[6:7], v[10:11], v[74:75] op_sel_hi:[1,0,1]
	s_waitcnt vmcnt(8)
	v_pk_fma_f32 v[94:95], v[4:5], v[10:11], v[80:81] op_sel:[0,1,0]
	v_pk_fma_f32 v[96:97], v[2:3], v[10:11], v[18:19] op_sel:[0,1,0]
	v_mov_b32_e32 v10, v13
	v_pk_fma_f32 v[100:101], v[6:7], v[12:13], v[56:57] op_sel_hi:[1,0,1]
	v_pk_fma_f32 v[102:103], v[4:5], v[10:11], v[82:83] op_sel_hi:[1,0,1]
	s_waitcnt lgkmcnt(0)
	v_pk_fma_f32 v[108:109], v[6:7], v[14:15], v[58:59] op_sel_hi:[1,0,1]
	v_pk_fma_f32 v[110:111], v[6:7], v[16:17], v[64:65] op_sel_hi:[1,0,1]
	global_load_dwordx4 v[72:75], v[112:113], off nt
	global_load_dwordx4 v[80:83], v[112:113], off offset:1024 nt
	global_load_dwordx4 v[64:67], v[112:113], off offset:2048 nt
	global_load_dwordx4 v[56:59], v[112:113], off offset:3072 nt
	v_mov_b32_e32 v6, v17
	v_pk_fma_f32 v[104:105], v[2:3], v[10:11], v[20:21] op_sel_hi:[1,0,1]
	v_pk_fma_f32 v[22:23], v[2:3], v[14:15], v[22:23] op_sel:[0,1,0]
	v_pk_fma_f32 v[32:33], v[2:3], v[6:7], v[32:33] op_sel_hi:[1,0,1]
	v_add_co_u32_e32 v2, vcc, s0, v86
	s_mov_b32 s0, 0x8000
	s_nop 0
	v_addc_co_u32_e32 v3, vcc, 0, v87, vcc
	v_add_co_u32_e32 v112, vcc, s0, v86
	v_pk_fma_f32 v[98:99], v[8:9], v[12:13], v[26:27] op_sel_hi:[1,0,1]
	s_nop 0
	v_addc_co_u32_e32 v113, vcc, 0, v87, vcc
	v_pk_fma_f32 v[106:107], v[8:9], v[14:15], v[28:29] op_sel_hi:[1,0,1]
	v_pk_fma_f32 v[88:89], v[4:5], v[14:15], v[88:89] op_sel:[0,1,0]
	v_pk_fma_f32 v[24:25], v[4:5], v[6:7], v[24:25] op_sel_hi:[1,0,1]
	global_load_dwordx4 v[26:29], v[112:113], off offset:-4096 nt
	global_load_dwordx4 v[18:21], v[2:3], off offset:1024 nt
	global_load_dwordx4 v[10:13], v[2:3], off offset:2048 nt
	s_nop 0
	global_load_dwordx4 v[2:5], v[2:3], off offset:3072 nt
	v_pk_fma_f32 v[30:31], v[8:9], v[16:17], v[30:31] op_sel_hi:[1,0,1]
	ds_read_b128 v[6:9], v34 offset:16896
	ds_read_b128 v[14:17], v34 offset:16912
	s_mov_b32 s0, 0x9000
	s_waitcnt vmcnt(15) lgkmcnt(1)
	v_pk_fma_f32 v[90:91], v[70:71], v[6:7], v[90:91] op_sel_hi:[1,0,1]
	v_pk_fma_f32 v[92:93], v[68:69], v[6:7], v[92:93] op_sel_hi:[1,0,1]
	s_waitcnt vmcnt(14)
	v_pk_fma_f32 v[94:95], v[78:79], v[6:7], v[94:95] op_sel:[0,1,0]
	v_pk_fma_f32 v[96:97], v[76:77], v[6:7], v[96:97] op_sel:[0,1,0]
	v_mov_b32_e32 v6, v9
	v_pk_fma_f32 v[102:103], v[78:79], v[6:7], v[102:103] op_sel_hi:[1,0,1]
	v_pk_fma_f32 v[104:105], v[76:77], v[6:7], v[104:105] op_sel_hi:[1,0,1]
	s_waitcnt lgkmcnt(0)
	v_mov_b32_e32 v6, v17
	v_pk_fma_f32 v[98:99], v[70:71], v[8:9], v[98:99] op_sel_hi:[1,0,1]
	v_pk_fma_f32 v[100:101], v[68:69], v[8:9], v[100:101] op_sel_hi:[1,0,1]
	v_pk_fma_f32 v[106:107], v[70:71], v[14:15], v[106:107] op_sel_hi:[1,0,1]
	v_pk_fma_f32 v[108:109], v[68:69], v[14:15], v[108:109] op_sel_hi:[1,0,1]
	v_pk_fma_f32 v[88:89], v[78:79], v[14:15], v[88:89] op_sel:[0,1,0]
	v_pk_fma_f32 v[22:23], v[76:77], v[14:15], v[22:23] op_sel:[0,1,0]
	v_pk_fma_f32 v[30:31], v[70:71], v[16:17], v[30:31] op_sel_hi:[1,0,1]
	v_pk_fma_f32 v[68:69], v[68:69], v[16:17], v[110:111] op_sel_hi:[1,0,1]
	v_pk_fma_f32 v[24:25], v[78:79], v[6:7], v[24:25] op_sel_hi:[1,0,1]
	v_pk_fma_f32 v[32:33], v[76:77], v[6:7], v[32:33] op_sel_hi:[1,0,1]
	ds_read_b128 v[6:9], v34 offset:16960
	ds_read_b128 v[14:17], v34 offset:16976
	s_waitcnt vmcnt(13) lgkmcnt(1)
	v_pk_fma_f32 v[70:71], v[62:63], v[6:7], v[90:91] op_sel_hi:[1,0,1]
	v_pk_fma_f32 v[76:77], v[60:61], v[6:7], v[92:93] op_sel_hi:[1,0,1]
	s_waitcnt vmcnt(12)
	v_pk_fma_f32 v[78:79], v[54:55], v[6:7], v[94:95] op_sel:[0,1,0]
	v_pk_fma_f32 v[90:91], v[52:53], v[6:7], v[96:97] op_sel:[0,1,0]
	v_mov_b32_e32 v6, v9
	v_pk_fma_f32 v[92:93], v[62:63], v[8:9], v[98:99] op_sel_hi:[1,0,1]
	v_pk_fma_f32 v[96:97], v[54:55], v[6:7], v[102:103] op_sel_hi:[1,0,1]
	v_pk_fma_f32 v[98:99], v[52:53], v[6:7], v[104:105] op_sel_hi:[1,0,1]
	s_waitcnt lgkmcnt(0)
	v_mov_b32_e32 v6, v17
	v_pk_fma_f32 v[94:95], v[60:61], v[8:9], v[100:101] op_sel_hi:[1,0,1]
	v_pk_fma_f32 v[100:101], v[62:63], v[14:15], v[106:107] op_sel_hi:[1,0,1]
	v_pk_fma_f32 v[102:103], v[60:61], v[14:15], v[108:109] op_sel_hi:[1,0,1]
	v_pk_fma_f32 v[88:89], v[54:55], v[14:15], v[88:89] op_sel:[0,1,0]
	v_pk_fma_f32 v[22:23], v[52:53], v[14:15], v[22:23] op_sel:[0,1,0]
	v_pk_fma_f32 v[30:31], v[62:63], v[16:17], v[30:31] op_sel_hi:[1,0,1]
	v_pk_fma_f32 v[60:61], v[60:61], v[16:17], v[68:69] op_sel_hi:[1,0,1]
	v_pk_fma_f32 v[24:25], v[54:55], v[6:7], v[24:25] op_sel_hi:[1,0,1]
	v_pk_fma_f32 v[32:33], v[52:53], v[6:7], v[32:33] op_sel_hi:[1,0,1]
	ds_read_b128 v[6:9], v34 offset:17024
	ds_read_b128 v[14:17], v34 offset:17040
	s_waitcnt vmcnt(11) lgkmcnt(1)
; #define DEC_LOADV(dst, i0) do { asm volatile("" ::: "memory"); _Pragma("unroll") for (int u = 0; u < 4; ++u) { const float* vr = cv + rbase + (size_t)((i0) + u) * 512; dst[u][0] = __builtin_nontemporal_load((const f32x4*)(vr + 4 * lane)); dst[u][1] = __builtin_nontemporal_load((const f32x4*)(vr + 256 + 4 * lane)); } } while (0)
; __device__ __forceinline__ void decode_item(Frame& F, const Args& a, int l, int item, unsigned char* ws) {
;     ...
;     const int hh = lane >> 5;
;     {
;         f32x4 va[4][2], vb[4][2];
;     ...
;         DEC_LOADV(va, 0); DEC_LOADV(vb, 4); DEC_ACC(va, 0); DEC_LOADV(va, 8); DEC_ACC(vb, 4); DEC_LOADV(vb, 12); DEC_ACC(va, 8); DEC_LOADV(va, 16); DEC_ACC(vb, 12); DEC_LOADV(vb, 20); DEC_ACC(va, 16); DEC_LOADV(va, 24); DEC_ACC(vb, 20); DEC_LOADV(vb, 28); DEC_ACC(va, 24); DEC_ACC(vb, 28);
	v_pk_fma_f32 v[52:53], v[50:51], v[6:7], v[70:71] op_sel_hi:[1,0,1]
	v_pk_fma_f32 v[54:55], v[48:49], v[6:7], v[76:77] op_sel_hi:[1,0,1]
	s_waitcnt vmcnt(10)
	v_pk_fma_f32 v[62:63], v[46:47], v[6:7], v[78:79] op_sel:[0,1,0]
	v_pk_fma_f32 v[68:69], v[44:45], v[6:7], v[90:91] op_sel:[0,1,0]
	v_mov_b32_e32 v6, v9
	v_pk_fma_f32 v[78:79], v[46:47], v[6:7], v[96:97] op_sel_hi:[1,0,1]
	v_pk_fma_f32 v[90:91], v[44:45], v[6:7], v[98:99] op_sel_hi:[1,0,1]
	s_waitcnt lgkmcnt(0)
	v_mov_b32_e32 v6, v17
	v_pk_fma_f32 v[70:71], v[50:51], v[8:9], v[92:93] op_sel_hi:[1,0,1]
	v_pk_fma_f32 v[76:77], v[48:49], v[8:9], v[94:95] op_sel_hi:[1,0,1]
	v_pk_fma_f32 v[92:93], v[50:51], v[14:15], v[100:101] op_sel_hi:[1,0,1]
	v_pk_fma_f32 v[94:95], v[48:49], v[14:15], v[102:103] op_sel_hi:[1,0,1]
	v_pk_fma_f32 v[88:89], v[46:47], v[14:15], v[88:89] op_sel:[0,1,0]
	v_pk_fma_f32 v[22:23], v[44:45], v[14:15], v[22:23] op_sel:[0,1,0]
	v_pk_fma_f32 v[30:31], v[50:51], v[16:17], v[30:31] op_sel_hi:[1,0,1]
	v_pk_fma_f32 v[48:49], v[48:49], v[16:17], v[60:61] op_sel_hi:[1,0,1]
	v_pk_fma_f32 v[24:25], v[46:47], v[6:7], v[24:25] op_sel_hi:[1,0,1]
	v_pk_fma_f32 v[32:33], v[44:45], v[6:7], v[32:33] op_sel_hi:[1,0,1]
	ds_read_b128 v[6:9], v34 offset:17088
	ds_read_b128 v[14:17], v34 offset:17104
	s_waitcnt vmcnt(9) lgkmcnt(1)
	v_pk_fma_f32 v[96:97], v[42:43], v[6:7], v[52:53] op_sel_hi:[1,0,1]
	v_pk_fma_f32 v[98:99], v[40:41], v[6:7], v[54:55] op_sel_hi:[1,0,1]
	s_waitcnt vmcnt(8)
	v_pk_fma_f32 v[100:101], v[38:39], v[6:7], v[62:63] op_sel:[0,1,0]
	v_pk_fma_f32 v[68:69], v[36:37], v[6:7], v[68:69] op_sel:[0,1,0]
	v_mov_b32_e32 v6, v9
	v_pk_fma_f32 v[78:79], v[38:39], v[6:7], v[78:79] op_sel_hi:[1,0,1]
	v_pk_fma_f32 v[90:91], v[36:37], v[6:7], v[90:91] op_sel_hi:[1,0,1]
	s_waitcnt lgkmcnt(0)
	v_mov_b32_e32 v6, v17
	v_pk_fma_f32 v[88:89], v[38:39], v[14:15], v[88:89] op_sel:[0,1,0]
	v_pk_fma_f32 v[102:103], v[36:37], v[14:15], v[22:23] op_sel:[0,1,0]
	v_pk_fma_f32 v[108:109], v[38:39], v[6:7], v[24:25] op_sel_hi:[1,0,1]
	v_pk_fma_f32 v[110:111], v[36:37], v[6:7], v[32:33] op_sel_hi:[1,0,1]
	global_load_dwordx4 v[52:55], v[112:113], off nt
	global_load_dwordx4 v[60:63], v[112:113], off offset:1024 nt
	global_load_dwordx4 v[44:47], v[112:113], off offset:2048 nt
	global_load_dwordx4 v[36:39], v[112:113], off offset:3072 nt
	v_add_co_u32_e32 v6, vcc, s0, v86
	s_mov_b32 s0, 0xa000
	s_nop 0
	v_addc_co_u32_e32 v7, vcc, 0, v87, vcc
	v_add_co_u32_e32 v112, vcc, s0, v86
	v_pk_fma_f32 v[70:71], v[42:43], v[8:9], v[70:71] op_sel_hi:[1,0,1]
	s_nop 0
	v_addc_co_u32_e32 v113, vcc, 0, v87, vcc
	v_pk_fma_f32 v[76:77], v[40:41], v[8:9], v[76:77] op_sel_hi:[1,0,1]
	v_pk_fma_f32 v[92:93], v[42:43], v[14:15], v[92:93] op_sel_hi:[1,0,1]
	v_pk_fma_f32 v[94:95], v[40:41], v[14:15], v[94:95] op_sel_hi:[1,0,1]
	v_pk_fma_f32 v[104:105], v[42:43], v[16:17], v[30:31] op_sel_hi:[1,0,1]
	v_pk_fma_f32 v[106:107], v[40:41], v[16:17], v[48:49] op_sel_hi:[1,0,1]
	global_load_dwordx4 v[30:33], v[112:113], off offset:-4096 nt
	global_load_dwordx4 v[22:25], v[6:7], off offset:1024 nt
	global_load_dwordx4 v[14:17], v[6:7], off offset:2048 nt
	s_nop 0
	global_load_dwordx4 v[6:9], v[6:7], off offset:3072 nt
	ds_read_b128 v[40:43], v34 offset:17152
	ds_read_b128 v[48:51], v34 offset:17168
	s_mov_b32 s0, 0xb000
	s_waitcnt vmcnt(15) lgkmcnt(1)
	v_pk_fma_f32 v[96:97], v[74:75], v[40:41], v[96:97] op_sel_hi:[1,0,1]
	v_pk_fma_f32 v[98:99], v[72:73], v[40:41], v[98:99] op_sel_hi:[1,0,1]
	s_waitcnt vmcnt(14)
	v_pk_fma_f32 v[100:101], v[82:83], v[40:41], v[100:101] op_sel:[0,1,0]
	v_pk_fma_f32 v[68:69], v[80:81], v[40:41], v[68:69] op_sel:[0,1,0]
	v_mov_b32_e32 v40, v43
	v_pk_fma_f32 v[78:79], v[82:83], v[40:41], v[78:79] op_sel_hi:[1,0,1]
	v_pk_fma_f32 v[90:91], v[80:81], v[40:41], v[90:91] op_sel_hi:[1,0,1]
	s_waitcnt lgkmcnt(0)
	v_mov_b32_e32 v40, v51
	v_pk_fma_f32 v[70:71], v[74:75], v[42:43], v[70:71] op_sel_hi:[1,0,1]
	v_pk_fma_f32 v[76:77], v[72:73], v[42:43], v[76:77] op_sel_hi:[1,0,1]
	v_pk_fma_f32 v[92:93], v[74:75], v[48:49], v[92:93] op_sel_hi:[1,0,1]
	v_pk_fma_f32 v[94:95], v[72:73], v[48:49], v[94:95] op_sel_hi:[1,0,1]
	v_pk_fma_f32 v[88:89], v[82:83], v[48:49], v[88:89] op_sel:[0,1,0]
	v_pk_fma_f32 v[102:103], v[80:81], v[48:49], v[102:103] op_sel:[0,1,0]
	v_pk_fma_f32 v[74:75], v[74:75], v[50:51], v[104:105] op_sel_hi:[1,0,1]
	v_pk_fma_f32 v[72:73], v[72:73], v[50:51], v[106:107] op_sel_hi:[1,0,1]
	v_pk_fma_f32 v[82:83], v[82:83], v[40:41], v[108:109] op_sel_hi:[1,0,1]
	v_pk_fma_f32 v[80:81], v[80:81], v[40:41], v[110:111] op_sel_hi:[1,0,1]
	ds_read_b128 v[40:43], v34 offset:17216
	ds_read_b128 v[48:51], v34 offset:17232
	s_waitcnt vmcnt(13) lgkmcnt(1)
	v_pk_fma_f32 v[96:97], v[66:67], v[40:41], v[96:97] op_sel_hi:[1,0,1]
	v_pk_fma_f32 v[98:99], v[64:65], v[40:41], v[98:99] op_sel_hi:[1,0,1]
	s_waitcnt vmcnt(12)
	v_pk_fma_f32 v[100:101], v[58:59], v[40:41], v[100:101] op_sel:[0,1,0]
	v_pk_fma_f32 v[68:69], v[56:57], v[40:41], v[68:69] op_sel:[0,1,0]
	v_mov_b32_e32 v40, v43
	v_pk_fma_f32 v[78:79], v[58:59], v[40:41], v[78:79] op_sel_hi:[1,0,1]
	v_pk_fma_f32 v[90:91], v[56:57], v[40:41], v[90:91] op_sel_hi:[1,0,1]
	s_waitcnt lgkmcnt(0)
	v_mov_b32_e32 v40, v51
	v_pk_fma_f32 v[70:71], v[66:67], v[42:43], v[70:71] op_sel_hi:[1,0,1]
	v_pk_fma_f32 v[76:77], v[64:65], v[42:43], v[76:77] op_sel_hi:[1,0,1]
	v_pk_fma_f32 v[92:93], v[66:67], v[48:49], v[92:93] op_sel_hi:[1,0,1]
	v_pk_fma_f32 v[94:95], v[64:65], v[48:49], v[94:95] op_sel_hi:[1,0,1]
	v_pk_fma_f32 v[88:89], v[58:59], v[48:49], v[88:89] op_sel:[0,1,0]
	v_pk_fma_f32 v[102:103], v[56:57], v[48:49], v[102:103] op_sel:[0,1,0]
	v_pk_fma_f32 v[66:67], v[66:67], v[50:51], v[74:75] op_sel_hi:[1,0,1]
	v_pk_fma_f32 v[64:65], v[64:65], v[50:51], v[72:73] op_sel_hi:[1,0,1]
	v_pk_fma_f32 v[58:59], v[58:59], v[40:41], v[82:83] op_sel_hi:[1,0,1]
	v_pk_fma_f32 v[56:57], v[56:57], v[40:41], v[80:81] op_sel_hi:[1,0,1]
	ds_read_b128 v[40:43], v34 offset:17280
	ds_read_b128 v[48:51], v34 offset:17296
	s_waitcnt vmcnt(11) lgkmcnt(1)
; #define DEC_LOADV(dst, i0) do { asm volatile("" ::: "memory"); _Pragma("unroll") for (int u = 0; u < 4; ++u) { const float* vr = cv + rbase + (size_t)((i0) + u) * 512; dst[u][0] = __builtin_nontemporal_load((const f32x4*)(vr + 4 * lane)); dst[u][1] = __builtin_nontemporal_load((const f32x4*)(vr + 256 + 4 * lane)); } } while (0)
; __device__ __forceinline__ void decode_item(Frame& F, const Args& a, int l, int item, unsigned char* ws) {
;     ...
;     const int hh = lane >> 5;
;     {
;         f32x4 va[4][2], vb[4][2];
;     ...
;         DEC_LOADV(va, 0); DEC_LOADV(vb, 4); DEC_ACC(va, 0); DEC_LOADV(va, 8); DEC_ACC(vb, 4); DEC_LOADV(vb, 12); DEC_ACC(va, 8); DEC_LOADV(va, 16); DEC_ACC(vb, 12); DEC_LOADV(vb, 20); DEC_ACC(va, 16); DEC_LOADV(va, 24); DEC_ACC(vb, 20); DEC_LOADV(vb, 28); DEC_ACC(va, 24); DEC_ACC(vb, 28);
	v_pk_fma_f32 v[72:73], v[28:29], v[40:41], v[96:97] op_sel_hi:[1,0,1]
	v_pk_fma_f32 v[74:75], v[26:27], v[40:41], v[98:99] op_sel_hi:[1,0,1]
	s_waitcnt vmcnt(10)
	v_pk_fma_f32 v[80:81], v[20:21], v[40:41], v[100:101] op_sel:[0,1,0]
	v_pk_fma_f32 v[40:41], v[18:19], v[40:41], v[68:69] op_sel:[0,1,0]
	v_pk_fma_f32 v[68:69], v[28:29], v[42:43], v[70:71] op_sel_hi:[1,0,1]
	v_pk_fma_f32 v[70:71], v[26:27], v[42:43], v[76:77] op_sel_hi:[1,0,1]
	v_mov_b32_e32 v42, v43
	s_waitcnt lgkmcnt(0)
	v_pk_fma_f32 v[82:83], v[26:27], v[48:49], v[94:95] op_sel_hi:[1,0,1]
	v_pk_fma_f32 v[64:65], v[26:27], v[50:51], v[64:65] op_sel_hi:[1,0,1]
	v_mov_b32_e32 v26, v51
	v_pk_fma_f32 v[76:77], v[20:21], v[42:43], v[78:79] op_sel_hi:[1,0,1]
	v_pk_fma_f32 v[42:43], v[18:19], v[42:43], v[90:91] op_sel_hi:[1,0,1]
	v_pk_fma_f32 v[78:79], v[28:29], v[48:49], v[92:93] op_sel_hi:[1,0,1]
	v_pk_fma_f32 v[88:89], v[20:21], v[48:49], v[88:89] op_sel:[0,1,0]
	v_pk_fma_f32 v[48:49], v[18:19], v[48:49], v[102:103] op_sel:[0,1,0]
	v_pk_fma_f32 v[66:67], v[28:29], v[50:51], v[66:67] op_sel_hi:[1,0,1]
	v_pk_fma_f32 v[50:51], v[20:21], v[26:27], v[58:59] op_sel_hi:[1,0,1]
	v_pk_fma_f32 v[56:57], v[18:19], v[26:27], v[56:57] op_sel_hi:[1,0,1]
	ds_read_b128 v[18:21], v34 offset:17344
	ds_read_b128 v[26:29], v34 offset:17360
	s_waitcnt vmcnt(9) lgkmcnt(1)
	v_pk_fma_f32 v[90:91], v[12:13], v[18:19], v[72:73] op_sel_hi:[1,0,1]
	v_pk_fma_f32 v[92:93], v[10:11], v[18:19], v[74:75] op_sel_hi:[1,0,1]
	s_waitcnt vmcnt(8)
	v_pk_fma_f32 v[80:81], v[4:5], v[18:19], v[80:81] op_sel:[0,1,0]
	v_pk_fma_f32 v[94:95], v[2:3], v[18:19], v[40:41] op_sel:[0,1,0]
	v_pk_fma_f32 v[98:99], v[10:11], v[20:21], v[70:71] op_sel_hi:[1,0,1]
	v_mov_b32_e32 v18, v21
	s_waitcnt lgkmcnt(0)
	v_pk_fma_f32 v[82:83], v[10:11], v[26:27], v[82:83] op_sel_hi:[1,0,1]
	v_pk_fma_f32 v[106:107], v[10:11], v[28:29], v[64:65] op_sel_hi:[1,0,1]
	v_mov_b32_e32 v10, v29
	v_pk_fma_f32 v[100:101], v[2:3], v[18:19], v[42:43] op_sel_hi:[1,0,1]
	v_pk_fma_f32 v[102:103], v[2:3], v[26:27], v[48:49] op_sel:[0,1,0]
	v_pk_fma_f32 v[104:105], v[12:13], v[28:29], v[66:67] op_sel_hi:[1,0,1]
	v_pk_fma_f32 v[108:109], v[4:5], v[10:11], v[50:51] op_sel_hi:[1,0,1]
	v_pk_fma_f32 v[110:111], v[2:3], v[10:11], v[56:57] op_sel_hi:[1,0,1]
	global_load_dwordx4 v[56:59], v[112:113], off nt
	global_load_dwordx4 v[64:67], v[112:113], off offset:1024 nt
	global_load_dwordx4 v[48:51], v[112:113], off offset:2048 nt
	global_load_dwordx4 v[40:43], v[112:113], off offset:3072 nt
	v_add_co_u32_e32 v2, vcc, s0, v86
	s_mov_b32 s0, 0xc000
	s_nop 0
	v_addc_co_u32_e32 v3, vcc, 0, v87, vcc
	v_add_co_u32_e32 v112, vcc, s0, v86
	v_pk_fma_f32 v[96:97], v[12:13], v[20:21], v[68:69] op_sel_hi:[1,0,1]
	s_nop 0
	v_addc_co_u32_e32 v113, vcc, 0, v87, vcc
	v_pk_fma_f32 v[76:77], v[4:5], v[18:19], v[76:77] op_sel_hi:[1,0,1]
	v_pk_fma_f32 v[78:79], v[12:13], v[26:27], v[78:79] op_sel_hi:[1,0,1]
	v_pk_fma_f32 v[88:89], v[4:5], v[26:27], v[88:89] op_sel:[0,1,0]
	global_load_dwordx4 v[26:29], v[112:113], off offset:-4096 nt
	global_load_dwordx4 v[18:21], v[2:3], off offset:1024 nt
	global_load_dwordx4 v[10:13], v[2:3], off offset:2048 nt
	s_nop 0
	global_load_dwordx4 v[2:5], v[2:3], off offset:3072 nt
	ds_read_b128 v[68:71], v34 offset:17408
	ds_read_b128 v[72:75], v34 offset:17424
	s_mov_b32 s0, 0xd000
	s_waitcnt vmcnt(15) lgkmcnt(1)
	v_pk_fma_f32 v[90:91], v[54:55], v[68:69], v[90:91] op_sel_hi:[1,0,1]
	v_pk_fma_f32 v[92:93], v[52:53], v[68:69], v[92:93] op_sel_hi:[1,0,1]
	s_waitcnt vmcnt(14)
	v_pk_fma_f32 v[80:81], v[62:63], v[68:69], v[80:81] op_sel:[0,1,0]
	v_pk_fma_f32 v[68:69], v[60:61], v[68:69], v[94:95] op_sel:[0,1,0]
	v_pk_fma_f32 v[94:95], v[54:55], v[70:71], v[96:97] op_sel_hi:[1,0,1]
	v_pk_fma_f32 v[96:97], v[52:53], v[70:71], v[98:99] op_sel_hi:[1,0,1]
	v_mov_b32_e32 v70, v71
	v_pk_fma_f32 v[76:77], v[62:63], v[70:71], v[76:77] op_sel_hi:[1,0,1]
	v_pk_fma_f32 v[70:71], v[60:61], v[70:71], v[100:101] op_sel_hi:[1,0,1]
	s_waitcnt lgkmcnt(0)
	v_pk_fma_f32 v[82:83], v[52:53], v[72:73], v[82:83] op_sel_hi:[1,0,1]
	v_pk_fma_f32 v[100:101], v[52:53], v[74:75], v[106:107] op_sel_hi:[1,0,1]
	v_mov_b32_e32 v52, v75
	v_pk_fma_f32 v[78:79], v[54:55], v[72:73], v[78:79] op_sel_hi:[1,0,1]
	v_pk_fma_f32 v[88:89], v[62:63], v[72:73], v[88:89] op_sel:[0,1,0]
	v_pk_fma_f32 v[72:73], v[60:61], v[72:73], v[102:103] op_sel:[0,1,0]
	v_pk_fma_f32 v[98:99], v[54:55], v[74:75], v[104:105] op_sel_hi:[1,0,1]
	v_pk_fma_f32 v[74:75], v[62:63], v[52:53], v[108:109] op_sel_hi:[1,0,1]
	v_pk_fma_f32 v[102:103], v[60:61], v[52:53], v[110:111] op_sel_hi:[1,0,1]
	ds_read_b128 v[52:55], v34 offset:17472
	ds_read_b128 v[60:63], v34 offset:17488
	s_waitcnt vmcnt(13) lgkmcnt(1)
	v_pk_fma_f32 v[90:91], v[46:47], v[52:53], v[90:91] op_sel_hi:[1,0,1]
	v_pk_fma_f32 v[92:93], v[44:45], v[52:53], v[92:93] op_sel_hi:[1,0,1]
	s_waitcnt vmcnt(12)
	v_pk_fma_f32 v[80:81], v[38:39], v[52:53], v[80:81] op_sel:[0,1,0]
	v_pk_fma_f32 v[52:53], v[36:37], v[52:53], v[68:69] op_sel:[0,1,0]
	v_pk_fma_f32 v[68:69], v[46:47], v[54:55], v[94:95] op_sel_hi:[1,0,1]
	v_pk_fma_f32 v[94:95], v[44:45], v[54:55], v[96:97] op_sel_hi:[1,0,1]
	v_mov_b32_e32 v54, v55
	v_pk_fma_f32 v[76:77], v[38:39], v[54:55], v[76:77] op_sel_hi:[1,0,1]
	v_pk_fma_f32 v[54:55], v[36:37], v[54:55], v[70:71] op_sel_hi:[1,0,1]
	s_waitcnt lgkmcnt(0)
; #define DEC_LOADV(dst, i0) do { asm volatile("" ::: "memory"); _Pragma("unroll") for (int u = 0; u < 4; ++u) { const float* vr = cv + rbase + (size_t)((i0) + u) * 512; dst[u][0] = __builtin_nontemporal_load((const f32x4*)(vr + 4 * lane)); dst[u][1] = __builtin_nontemporal_load((const f32x4*)(vr + 256 + 4 * lane)); } } while (0)
; __device__ __forceinline__ void decode_item(Frame& F, const Args& a, int l, int item, unsigned char* ws) {
;     ...
;     const int hh = lane >> 5;
;     {
;         f32x4 va[4][2], vb[4][2];
;     ...
;         DEC_LOADV(va, 0); DEC_LOADV(vb, 4); DEC_ACC(va, 0); DEC_LOADV(va, 8); DEC_ACC(vb, 4); DEC_LOADV(vb, 12); DEC_ACC(va, 8); DEC_LOADV(va, 16); DEC_ACC(vb, 12); DEC_LOADV(vb, 20); DEC_ACC(va, 16); DEC_LOADV(va, 24); DEC_ACC(vb, 20); DEC_LOADV(vb, 28); DEC_ACC(va, 24); DEC_ACC(vb, 28);
	v_pk_fma_f32 v[70:71], v[46:47], v[60:61], v[78:79] op_sel_hi:[1,0,1]
	v_pk_fma_f32 v[78:79], v[44:45], v[60:61], v[82:83] op_sel_hi:[1,0,1]
	v_pk_fma_f32 v[82:83], v[38:39], v[60:61], v[88:89] op_sel:[0,1,0]
	v_pk_fma_f32 v[88:89], v[44:45], v[62:63], v[100:101] op_sel_hi:[1,0,1]
	v_mov_b32_e32 v44, v63
	v_pk_fma_f32 v[60:61], v[36:37], v[60:61], v[72:73] op_sel:[0,1,0]
	v_pk_fma_f32 v[72:73], v[46:47], v[62:63], v[98:99] op_sel_hi:[1,0,1]
	v_pk_fma_f32 v[62:63], v[38:39], v[44:45], v[74:75] op_sel_hi:[1,0,1]
	v_pk_fma_f32 v[74:75], v[36:37], v[44:45], v[102:103] op_sel_hi:[1,0,1]
	ds_read_b128 v[36:39], v34 offset:17536
	ds_read_b128 v[44:47], v34 offset:17552
	s_waitcnt vmcnt(11) lgkmcnt(1)
	v_pk_fma_f32 v[90:91], v[32:33], v[36:37], v[90:91] op_sel_hi:[1,0,1]
	v_pk_fma_f32 v[92:93], v[30:31], v[36:37], v[92:93] op_sel_hi:[1,0,1]
	s_waitcnt vmcnt(10)
	v_pk_fma_f32 v[80:81], v[24:25], v[36:37], v[80:81] op_sel:[0,1,0]
	v_pk_fma_f32 v[36:37], v[22:23], v[36:37], v[52:53] op_sel:[0,1,0]
	v_pk_fma_f32 v[52:53], v[32:33], v[38:39], v[68:69] op_sel_hi:[1,0,1]
	v_pk_fma_f32 v[68:69], v[30:31], v[38:39], v[94:95] op_sel_hi:[1,0,1]
	v_mov_b32_e32 v38, v39
	v_pk_fma_f32 v[76:77], v[24:25], v[38:39], v[76:77] op_sel_hi:[1,0,1]
	v_pk_fma_f32 v[38:39], v[22:23], v[38:39], v[54:55] op_sel_hi:[1,0,1]
	s_waitcnt lgkmcnt(0)
	v_pk_fma_f32 v[54:55], v[32:33], v[44:45], v[70:71] op_sel_hi:[1,0,1]
	v_pk_fma_f32 v[70:71], v[30:31], v[44:45], v[78:79] op_sel_hi:[1,0,1]
	v_pk_fma_f32 v[78:79], v[24:25], v[44:45], v[82:83] op_sel:[0,1,0]
	v_pk_fma_f32 v[44:45], v[22:23], v[44:45], v[60:61] op_sel:[0,1,0]
	v_pk_fma_f32 v[60:61], v[32:33], v[46:47], v[72:73] op_sel_hi:[1,0,1]
	v_pk_fma_f32 v[72:73], v[30:31], v[46:47], v[88:89] op_sel_hi:[1,0,1]
	v_mov_b32_e32 v30, v47
	v_pk_fma_f32 v[46:47], v[24:25], v[30:31], v[62:63] op_sel_hi:[1,0,1]
	v_pk_fma_f32 v[62:63], v[22:23], v[30:31], v[74:75] op_sel_hi:[1,0,1]
	ds_read_b128 v[22:25], v34 offset:17600
	ds_read_b128 v[30:33], v34 offset:17616
	s_waitcnt vmcnt(9) lgkmcnt(1)
	v_pk_fma_f32 v[82:83], v[16:17], v[22:23], v[90:91] op_sel_hi:[1,0,1]
	v_pk_fma_f32 v[88:89], v[14:15], v[22:23], v[92:93] op_sel_hi:[1,0,1]
	s_waitcnt vmcnt(8)
	v_pk_fma_f32 v[80:81], v[8:9], v[22:23], v[80:81] op_sel:[0,1,0]
	v_pk_fma_f32 v[90:91], v[6:7], v[22:23], v[36:37] op_sel:[0,1,0]
	v_pk_fma_f32 v[94:95], v[14:15], v[24:25], v[68:69] op_sel_hi:[1,0,1]
	v_mov_b32_e32 v22, v25
	s_waitcnt lgkmcnt(0)
	v_pk_fma_f32 v[100:101], v[14:15], v[30:31], v[70:71] op_sel_hi:[1,0,1]
	v_pk_fma_f32 v[106:107], v[14:15], v[32:33], v[72:73] op_sel_hi:[1,0,1]
	v_mov_b32_e32 v14, v33
	v_pk_fma_f32 v[96:97], v[6:7], v[22:23], v[38:39] op_sel_hi:[1,0,1]
	v_pk_fma_f32 v[102:103], v[6:7], v[30:31], v[44:45] op_sel:[0,1,0]
	v_pk_fma_f32 v[110:111], v[6:7], v[14:15], v[62:63] op_sel_hi:[1,0,1]
	v_add_co_u32_e32 v6, vcc, s0, v86
	s_mov_b32 s0, 0xe000
	s_nop 0
	v_addc_co_u32_e32 v7, vcc, 0, v87, vcc
	v_pk_fma_f32 v[92:93], v[16:17], v[24:25], v[52:53] op_sel_hi:[1,0,1]
	v_pk_fma_f32 v[98:99], v[16:17], v[30:31], v[54:55] op_sel_hi:[1,0,1]
	v_pk_fma_f32 v[104:105], v[16:17], v[32:33], v[60:61] op_sel_hi:[1,0,1]
	v_pk_fma_f32 v[108:109], v[8:9], v[14:15], v[46:47] op_sel_hi:[1,0,1]
	global_load_dwordx4 v[52:55], v[112:113], off nt
	global_load_dwordx4 v[60:63], v[112:113], off offset:1024 nt
	global_load_dwordx4 v[44:47], v[112:113], off offset:2048 nt
	global_load_dwordx4 v[36:39], v[112:113], off offset:3072 nt
	v_add_co_u32_e32 v112, vcc, s0, v86
	v_pk_fma_f32 v[76:77], v[8:9], v[22:23], v[76:77] op_sel_hi:[1,0,1]
	s_nop 0
	v_addc_co_u32_e32 v113, vcc, 0, v87, vcc
	v_pk_fma_f32 v[78:79], v[8:9], v[30:31], v[78:79] op_sel:[0,1,0]
	global_load_dwordx4 v[30:33], v[112:113], off offset:-4096 nt
	global_load_dwordx4 v[22:25], v[6:7], off offset:1024 nt
	global_load_dwordx4 v[14:17], v[6:7], off offset:2048 nt
	s_nop 0
	global_load_dwordx4 v[6:9], v[6:7], off offset:3072 nt
	ds_read_b128 v[68:71], v34 offset:17664
	ds_read_b128 v[72:75], v34 offset:17680
	s_mov_b32 s0, 0xf000
	s_waitcnt vmcnt(15) lgkmcnt(1)
	v_pk_fma_f32 v[82:83], v[58:59], v[68:69], v[82:83] op_sel_hi:[1,0,1]
	v_pk_fma_f32 v[88:89], v[56:57], v[68:69], v[88:89] op_sel_hi:[1,0,1]
	s_waitcnt vmcnt(14)
	v_pk_fma_f32 v[80:81], v[66:67], v[68:69], v[80:81] op_sel:[0,1,0]
	v_pk_fma_f32 v[68:69], v[64:65], v[68:69], v[90:91] op_sel:[0,1,0]
	v_pk_fma_f32 v[90:91], v[58:59], v[70:71], v[92:93] op_sel_hi:[1,0,1]
	v_pk_fma_f32 v[92:93], v[56:57], v[70:71], v[94:95] op_sel_hi:[1,0,1]
	v_mov_b32_e32 v70, v71
	v_pk_fma_f32 v[76:77], v[66:67], v[70:71], v[76:77] op_sel_hi:[1,0,1]
	v_pk_fma_f32 v[70:71], v[64:65], v[70:71], v[96:97] op_sel_hi:[1,0,1]
	s_waitcnt lgkmcnt(0)
	v_pk_fma_f32 v[96:97], v[56:57], v[72:73], v[100:101] op_sel_hi:[1,0,1]
	v_pk_fma_f32 v[100:101], v[56:57], v[74:75], v[106:107] op_sel_hi:[1,0,1]
	v_mov_b32_e32 v56, v75
	v_pk_fma_f32 v[94:95], v[58:59], v[72:73], v[98:99] op_sel_hi:[1,0,1]
	v_pk_fma_f32 v[78:79], v[66:67], v[72:73], v[78:79] op_sel:[0,1,0]
	v_pk_fma_f32 v[72:73], v[64:65], v[72:73], v[102:103] op_sel:[0,1,0]
	v_pk_fma_f32 v[98:99], v[58:59], v[74:75], v[104:105] op_sel_hi:[1,0,1]
	v_pk_fma_f32 v[74:75], v[66:67], v[56:57], v[108:109] op_sel_hi:[1,0,1]
	v_pk_fma_f32 v[102:103], v[64:65], v[56:57], v[110:111] op_sel_hi:[1,0,1]
	ds_read_b128 v[56:59], v34 offset:17728
	ds_read_b128 v[64:67], v34 offset:17744
	s_waitcnt vmcnt(13) lgkmcnt(1)
	v_pk_fma_f32 v[82:83], v[50:51], v[56:57], v[82:83] op_sel_hi:[1,0,1]
	v_pk_fma_f32 v[88:89], v[48:49], v[56:57], v[88:89] op_sel_hi:[1,0,1]
	s_waitcnt vmcnt(12)
; #define DEC_LOADV(dst, i0) do { asm volatile("" ::: "memory"); _Pragma("unroll") for (int u = 0; u < 4; ++u) { const float* vr = cv + rbase + (size_t)((i0) + u) * 512; dst[u][0] = __builtin_nontemporal_load((const f32x4*)(vr + 4 * lane)); dst[u][1] = __builtin_nontemporal_load((const f32x4*)(vr + 256 + 4 * lane)); } } while (0)
; __device__ __forceinline__ void decode_item(Frame& F, const Args& a, int l, int item, unsigned char* ws) {
;     ...
;     const int hh = lane >> 5;
;     {
;         f32x4 va[4][2], vb[4][2];
;     ...
;         DEC_LOADV(va, 0); DEC_LOADV(vb, 4); DEC_ACC(va, 0); DEC_LOADV(va, 8); DEC_ACC(vb, 4); DEC_LOADV(vb, 12); DEC_ACC(va, 8); DEC_LOADV(va, 16); DEC_ACC(vb, 12); DEC_LOADV(vb, 20); DEC_ACC(va, 16); DEC_LOADV(va, 24); DEC_ACC(vb, 20); DEC_LOADV(vb, 28); DEC_ACC(va, 24); DEC_ACC(vb, 28);
	v_pk_fma_f32 v[80:81], v[42:43], v[56:57], v[80:81] op_sel:[0,1,0]
	v_pk_fma_f32 v[56:57], v[40:41], v[56:57], v[68:69] op_sel:[0,1,0]
	v_pk_fma_f32 v[68:69], v[50:51], v[58:59], v[90:91] op_sel_hi:[1,0,1]
	v_pk_fma_f32 v[90:91], v[48:49], v[58:59], v[92:93] op_sel_hi:[1,0,1]
	v_mov_b32_e32 v58, v59
	v_pk_fma_f32 v[76:77], v[42:43], v[58:59], v[76:77] op_sel_hi:[1,0,1]
	v_pk_fma_f32 v[58:59], v[40:41], v[58:59], v[70:71] op_sel_hi:[1,0,1]
	s_waitcnt lgkmcnt(0)
	v_pk_fma_f32 v[70:71], v[50:51], v[64:65], v[94:95] op_sel_hi:[1,0,1]
	v_pk_fma_f32 v[92:93], v[48:49], v[64:65], v[96:97] op_sel_hi:[1,0,1]
	v_pk_fma_f32 v[94:95], v[48:49], v[66:67], v[100:101] op_sel_hi:[1,0,1]
	v_mov_b32_e32 v48, v67
	v_pk_fma_f32 v[78:79], v[42:43], v[64:65], v[78:79] op_sel:[0,1,0]
	v_pk_fma_f32 v[64:65], v[40:41], v[64:65], v[72:73] op_sel:[0,1,0]
	v_pk_fma_f32 v[72:73], v[50:51], v[66:67], v[98:99] op_sel_hi:[1,0,1]
	v_pk_fma_f32 v[66:67], v[42:43], v[48:49], v[74:75] op_sel_hi:[1,0,1]
	v_pk_fma_f32 v[74:75], v[40:41], v[48:49], v[102:103] op_sel_hi:[1,0,1]
	ds_read_b128 v[40:43], v34 offset:17792
	ds_read_b128 v[48:51], v34 offset:17808
	s_waitcnt vmcnt(11) lgkmcnt(1)
	v_pk_fma_f32 v[82:83], v[28:29], v[40:41], v[82:83] op_sel_hi:[1,0,1]
	v_pk_fma_f32 v[88:89], v[26:27], v[40:41], v[88:89] op_sel_hi:[1,0,1]
	s_waitcnt vmcnt(10)
	v_pk_fma_f32 v[80:81], v[20:21], v[40:41], v[80:81] op_sel:[0,1,0]
	v_pk_fma_f32 v[40:41], v[18:19], v[40:41], v[56:57] op_sel:[0,1,0]
	v_pk_fma_f32 v[56:57], v[28:29], v[42:43], v[68:69] op_sel_hi:[1,0,1]
	v_pk_fma_f32 v[68:69], v[26:27], v[42:43], v[90:91] op_sel_hi:[1,0,1]
	v_mov_b32_e32 v42, v43
	v_pk_fma_f32 v[76:77], v[20:21], v[42:43], v[76:77] op_sel_hi:[1,0,1]
	v_pk_fma_f32 v[42:43], v[18:19], v[42:43], v[58:59] op_sel_hi:[1,0,1]
	s_waitcnt lgkmcnt(0)
	v_pk_fma_f32 v[58:59], v[28:29], v[48:49], v[70:71] op_sel_hi:[1,0,1]
	v_pk_fma_f32 v[70:71], v[26:27], v[48:49], v[92:93] op_sel_hi:[1,0,1]
	v_pk_fma_f32 v[78:79], v[20:21], v[48:49], v[78:79] op_sel:[0,1,0]
	v_pk_fma_f32 v[48:49], v[18:19], v[48:49], v[64:65] op_sel:[0,1,0]
	v_pk_fma_f32 v[64:65], v[28:29], v[50:51], v[72:73] op_sel_hi:[1,0,1]
	v_pk_fma_f32 v[72:73], v[26:27], v[50:51], v[94:95] op_sel_hi:[1,0,1]
	v_mov_b32_e32 v26, v51
	v_pk_fma_f32 v[50:51], v[20:21], v[26:27], v[66:67] op_sel_hi:[1,0,1]
	v_pk_fma_f32 v[66:67], v[18:19], v[26:27], v[74:75] op_sel_hi:[1,0,1]
	ds_read_b128 v[18:21], v34 offset:17856
	ds_read_b128 v[26:29], v34 offset:17872
	s_waitcnt vmcnt(9) lgkmcnt(1)
	v_pk_fma_f32 v[82:83], v[12:13], v[18:19], v[82:83] op_sel_hi:[1,0,1]
	v_pk_fma_f32 v[88:89], v[10:11], v[18:19], v[88:89] op_sel_hi:[1,0,1]
	s_waitcnt vmcnt(8)
	v_pk_fma_f32 v[80:81], v[4:5], v[18:19], v[80:81] op_sel:[0,1,0]
	v_pk_fma_f32 v[90:91], v[2:3], v[18:19], v[40:41] op_sel:[0,1,0]
	v_pk_fma_f32 v[94:95], v[10:11], v[20:21], v[68:69] op_sel_hi:[1,0,1]
	v_mov_b32_e32 v18, v21
	s_waitcnt lgkmcnt(0)
	v_pk_fma_f32 v[100:101], v[10:11], v[26:27], v[70:71] op_sel_hi:[1,0,1]
	v_pk_fma_f32 v[106:107], v[10:11], v[28:29], v[72:73] op_sel_hi:[1,0,1]
	v_mov_b32_e32 v10, v29
	v_pk_fma_f32 v[92:93], v[12:13], v[20:21], v[56:57] op_sel_hi:[1,0,1]
	v_pk_fma_f32 v[96:97], v[2:3], v[18:19], v[42:43] op_sel_hi:[1,0,1]
	v_pk_fma_f32 v[98:99], v[12:13], v[26:27], v[58:59] op_sel_hi:[1,0,1]
	v_pk_fma_f32 v[102:103], v[2:3], v[26:27], v[48:49] op_sel:[0,1,0]
	v_pk_fma_f32 v[104:105], v[12:13], v[28:29], v[64:65] op_sel_hi:[1,0,1]
	v_pk_fma_f32 v[108:109], v[4:5], v[10:11], v[50:51] op_sel_hi:[1,0,1]
	v_pk_fma_f32 v[110:111], v[2:3], v[10:11], v[66:67] op_sel_hi:[1,0,1]
	global_load_dwordx4 v[64:67], v[112:113], off nt
	global_load_dwordx4 v[56:59], v[112:113], off offset:1024 nt
	global_load_dwordx4 v[48:51], v[112:113], off offset:2048 nt
	global_load_dwordx4 v[40:43], v[112:113], off offset:3072 nt
	v_add_co_u32_e32 v2, vcc, s0, v86
	v_pk_fma_f32 v[76:77], v[4:5], v[18:19], v[76:77] op_sel_hi:[1,0,1]
	s_nop 0
	v_addc_co_u32_e32 v3, vcc, 0, v87, vcc
	v_pk_fma_f32 v[78:79], v[4:5], v[26:27], v[78:79] op_sel:[0,1,0]
	global_load_dwordx4 v[26:29], v[2:3], off nt
	global_load_dwordx4 v[18:21], v[2:3], off offset:1024 nt
	global_load_dwordx4 v[10:13], v[2:3], off offset:2048 nt
	s_nop 0
	global_load_dwordx4 v[2:5], v[2:3], off offset:3072 nt
	ds_read_b128 v[68:71], v34 offset:17920
	ds_read_b128 v[72:75], v34 offset:17936
	s_waitcnt vmcnt(15) lgkmcnt(1)
	v_pk_fma_f32 v[82:83], v[54:55], v[68:69], v[82:83] op_sel_hi:[1,0,1]
	v_pk_fma_f32 v[86:87], v[52:53], v[68:69], v[88:89] op_sel_hi:[1,0,1]
	s_waitcnt vmcnt(14)
	v_pk_fma_f32 v[80:81], v[62:63], v[68:69], v[80:81] op_sel:[0,1,0]
	v_pk_fma_f32 v[68:69], v[60:61], v[68:69], v[90:91] op_sel:[0,1,0]
	v_pk_fma_f32 v[88:89], v[54:55], v[70:71], v[92:93] op_sel_hi:[1,0,1]
	v_pk_fma_f32 v[90:91], v[52:53], v[70:71], v[94:95] op_sel_hi:[1,0,1]
	v_mov_b32_e32 v70, v71
	s_waitcnt lgkmcnt(0)
	v_pk_fma_f32 v[92:93], v[54:55], v[72:73], v[98:99] op_sel_hi:[1,0,1]
	v_pk_fma_f32 v[94:95], v[52:53], v[72:73], v[100:101] op_sel_hi:[1,0,1]
	v_pk_fma_f32 v[98:99], v[52:53], v[74:75], v[106:107] op_sel_hi:[1,0,1]
	v_mov_b32_e32 v52, v75
	v_pk_fma_f32 v[76:77], v[62:63], v[70:71], v[76:77] op_sel_hi:[1,0,1]
	v_pk_fma_f32 v[70:71], v[60:61], v[70:71], v[96:97] op_sel_hi:[1,0,1]
	v_pk_fma_f32 v[78:79], v[62:63], v[72:73], v[78:79] op_sel:[0,1,0]
	v_pk_fma_f32 v[72:73], v[60:61], v[72:73], v[102:103] op_sel:[0,1,0]
	v_pk_fma_f32 v[96:97], v[54:55], v[74:75], v[104:105] op_sel_hi:[1,0,1]
	v_pk_fma_f32 v[74:75], v[62:63], v[52:53], v[108:109] op_sel_hi:[1,0,1]
	v_pk_fma_f32 v[100:101], v[60:61], v[52:53], v[110:111] op_sel_hi:[1,0,1]
	ds_read_b128 v[52:55], v34 offset:17984
	ds_read_b128 v[60:63], v34 offset:18000
	s_waitcnt vmcnt(13) lgkmcnt(1)
; #define DEC_LOADV(dst, i0) do { asm volatile("" ::: "memory"); _Pragma("unroll") for (int u = 0; u < 4; ++u) { const float* vr = cv + rbase + (size_t)((i0) + u) * 512; dst[u][0] = __builtin_nontemporal_load((const f32x4*)(vr + 4 * lane)); dst[u][1] = __builtin_nontemporal_load((const f32x4*)(vr + 256 + 4 * lane)); } } while (0)
; __device__ __forceinline__ void decode_item(Frame& F, const Args& a, int l, int item, unsigned char* ws) {
;     ...
;     const int hh = lane >> 5;
;     {
;         f32x4 va[4][2], vb[4][2];
;     ...
;         DEC_LOADV(va, 0); DEC_LOADV(vb, 4); DEC_ACC(va, 0); DEC_LOADV(va, 8); DEC_ACC(vb, 4); DEC_LOADV(vb, 12); DEC_ACC(va, 8); DEC_LOADV(va, 16); DEC_ACC(vb, 12); DEC_LOADV(vb, 20); DEC_ACC(va, 16); DEC_LOADV(va, 24); DEC_ACC(vb, 20); DEC_LOADV(vb, 28); DEC_ACC(va, 24); DEC_ACC(vb, 28);
	v_pk_fma_f32 v[82:83], v[46:47], v[52:53], v[82:83] op_sel_hi:[1,0,1]
	v_pk_fma_f32 v[86:87], v[44:45], v[52:53], v[86:87] op_sel_hi:[1,0,1]
	s_waitcnt vmcnt(12)
	v_pk_fma_f32 v[80:81], v[38:39], v[52:53], v[80:81] op_sel:[0,1,0]
	v_pk_fma_f32 v[52:53], v[36:37], v[52:53], v[68:69] op_sel:[0,1,0]
	v_pk_fma_f32 v[68:69], v[46:47], v[54:55], v[88:89] op_sel_hi:[1,0,1]
	v_pk_fma_f32 v[88:89], v[44:45], v[54:55], v[90:91] op_sel_hi:[1,0,1]
	v_mov_b32_e32 v54, v55
	v_pk_fma_f32 v[76:77], v[38:39], v[54:55], v[76:77] op_sel_hi:[1,0,1]
	v_pk_fma_f32 v[54:55], v[36:37], v[54:55], v[70:71] op_sel_hi:[1,0,1]
	s_waitcnt lgkmcnt(0)
	v_pk_fma_f32 v[70:71], v[46:47], v[60:61], v[92:93] op_sel_hi:[1,0,1]
	v_pk_fma_f32 v[90:91], v[44:45], v[60:61], v[94:95] op_sel_hi:[1,0,1]
	v_pk_fma_f32 v[92:93], v[44:45], v[62:63], v[98:99] op_sel_hi:[1,0,1]
	v_mov_b32_e32 v44, v63
	v_pk_fma_f32 v[78:79], v[38:39], v[60:61], v[78:79] op_sel:[0,1,0]
	v_pk_fma_f32 v[60:61], v[36:37], v[60:61], v[72:73] op_sel:[0,1,0]
	v_pk_fma_f32 v[72:73], v[46:47], v[62:63], v[96:97] op_sel_hi:[1,0,1]
	v_pk_fma_f32 v[62:63], v[38:39], v[44:45], v[74:75] op_sel_hi:[1,0,1]
	v_pk_fma_f32 v[74:75], v[36:37], v[44:45], v[100:101] op_sel_hi:[1,0,1]
	ds_read_b128 v[36:39], v34 offset:18048
	ds_read_b128 v[44:47], v34 offset:18064
	s_waitcnt vmcnt(11) lgkmcnt(1)
	v_pk_fma_f32 v[82:83], v[32:33], v[36:37], v[82:83] op_sel_hi:[1,0,1]
	v_pk_fma_f32 v[86:87], v[30:31], v[36:37], v[86:87] op_sel_hi:[1,0,1]
	s_waitcnt vmcnt(10)
	v_pk_fma_f32 v[80:81], v[24:25], v[36:37], v[80:81] op_sel:[0,1,0]
	v_pk_fma_f32 v[36:37], v[22:23], v[36:37], v[52:53] op_sel:[0,1,0]
	v_pk_fma_f32 v[52:53], v[32:33], v[38:39], v[68:69] op_sel_hi:[1,0,1]
	v_pk_fma_f32 v[68:69], v[30:31], v[38:39], v[88:89] op_sel_hi:[1,0,1]
	v_mov_b32_e32 v38, v39
	v_pk_fma_f32 v[76:77], v[24:25], v[38:39], v[76:77] op_sel_hi:[1,0,1]
	v_pk_fma_f32 v[38:39], v[22:23], v[38:39], v[54:55] op_sel_hi:[1,0,1]
	s_waitcnt lgkmcnt(0)
	v_pk_fma_f32 v[54:55], v[32:33], v[44:45], v[70:71] op_sel_hi:[1,0,1]
	v_pk_fma_f32 v[70:71], v[30:31], v[44:45], v[90:91] op_sel_hi:[1,0,1]
	v_pk_fma_f32 v[78:79], v[24:25], v[44:45], v[78:79] op_sel:[0,1,0]
	v_pk_fma_f32 v[44:45], v[22:23], v[44:45], v[60:61] op_sel:[0,1,0]
	v_pk_fma_f32 v[60:61], v[32:33], v[46:47], v[72:73] op_sel_hi:[1,0,1]
	v_pk_fma_f32 v[72:73], v[30:31], v[46:47], v[92:93] op_sel_hi:[1,0,1]
	v_mov_b32_e32 v30, v47
	v_pk_fma_f32 v[46:47], v[24:25], v[30:31], v[62:63] op_sel_hi:[1,0,1]
	v_pk_fma_f32 v[62:63], v[22:23], v[30:31], v[74:75] op_sel_hi:[1,0,1]
	ds_read_b128 v[22:25], v34 offset:18112
	ds_read_b128 v[30:33], v34 offset:18128
	s_waitcnt vmcnt(9) lgkmcnt(1)
	v_pk_fma_f32 v[74:75], v[16:17], v[22:23], v[82:83] op_sel_hi:[1,0,1]
	v_pk_fma_f32 v[82:83], v[14:15], v[22:23], v[86:87] op_sel_hi:[1,0,1]
	s_waitcnt vmcnt(8)
	v_pk_fma_f32 v[80:81], v[8:9], v[22:23], v[80:81] op_sel:[0,1,0]
	v_pk_fma_f32 v[22:23], v[6:7], v[22:23], v[36:37] op_sel:[0,1,0]
	v_pk_fma_f32 v[36:37], v[16:17], v[24:25], v[52:53] op_sel_hi:[1,0,1]
	v_pk_fma_f32 v[52:53], v[14:15], v[24:25], v[68:69] op_sel_hi:[1,0,1]
	v_mov_b32_e32 v24, v25
	v_pk_fma_f32 v[68:69], v[8:9], v[24:25], v[76:77] op_sel_hi:[1,0,1]
	v_pk_fma_f32 v[24:25], v[6:7], v[24:25], v[38:39] op_sel_hi:[1,0,1]
	s_waitcnt lgkmcnt(0)
	v_pk_fma_f32 v[38:39], v[16:17], v[30:31], v[54:55] op_sel_hi:[1,0,1]
	v_pk_fma_f32 v[54:55], v[14:15], v[30:31], v[70:71] op_sel_hi:[1,0,1]
	v_pk_fma_f32 v[70:71], v[8:9], v[30:31], v[78:79] op_sel:[0,1,0]
	v_pk_fma_f32 v[30:31], v[6:7], v[30:31], v[44:45] op_sel:[0,1,0]
	v_pk_fma_f32 v[44:45], v[16:17], v[32:33], v[60:61] op_sel_hi:[1,0,1]
	v_pk_fma_f32 v[60:61], v[14:15], v[32:33], v[72:73] op_sel_hi:[1,0,1]
	v_mov_b32_e32 v14, v33
	v_pk_fma_f32 v[32:33], v[8:9], v[14:15], v[46:47] op_sel_hi:[1,0,1]
	v_pk_fma_f32 v[46:47], v[6:7], v[14:15], v[62:63] op_sel_hi:[1,0,1]
	ds_read_b128 v[6:9], v34 offset:18176
	ds_read_b128 v[14:17], v34 offset:18192
	s_waitcnt vmcnt(7) lgkmcnt(1)
	v_pk_fma_f32 v[62:63], v[66:67], v[6:7], v[74:75] op_sel_hi:[1,0,1]
	v_pk_fma_f32 v[72:73], v[64:65], v[6:7], v[82:83] op_sel_hi:[1,0,1]
	s_waitcnt vmcnt(6)
	v_pk_fma_f32 v[74:75], v[58:59], v[6:7], v[80:81] op_sel:[0,1,0]
	v_pk_fma_f32 v[22:23], v[56:57], v[6:7], v[22:23] op_sel:[0,1,0]
	v_mov_b32_e32 v6, v9
	v_pk_fma_f32 v[68:69], v[58:59], v[6:7], v[68:69] op_sel_hi:[1,0,1]
	v_pk_fma_f32 v[24:25], v[56:57], v[6:7], v[24:25] op_sel_hi:[1,0,1]
	s_waitcnt lgkmcnt(0)
	v_mov_b32_e32 v6, v17
	v_pk_fma_f32 v[36:37], v[66:67], v[8:9], v[36:37] op_sel_hi:[1,0,1]
	v_pk_fma_f32 v[52:53], v[64:65], v[8:9], v[52:53] op_sel_hi:[1,0,1]
	v_pk_fma_f32 v[38:39], v[66:67], v[14:15], v[38:39] op_sel_hi:[1,0,1]
	v_pk_fma_f32 v[54:55], v[64:65], v[14:15], v[54:55] op_sel_hi:[1,0,1]
	v_pk_fma_f32 v[70:71], v[58:59], v[14:15], v[70:71] op_sel:[0,1,0]
	v_pk_fma_f32 v[30:31], v[56:57], v[14:15], v[30:31] op_sel:[0,1,0]
	v_pk_fma_f32 v[44:45], v[66:67], v[16:17], v[44:45] op_sel_hi:[1,0,1]
	v_pk_fma_f32 v[60:61], v[64:65], v[16:17], v[60:61] op_sel_hi:[1,0,1]
	v_pk_fma_f32 v[32:33], v[58:59], v[6:7], v[32:33] op_sel_hi:[1,0,1]
	v_pk_fma_f32 v[46:47], v[56:57], v[6:7], v[46:47] op_sel_hi:[1,0,1]
	ds_read_b128 v[6:9], v34 offset:18240
	ds_read_b128 v[14:17], v34 offset:18256
	s_waitcnt vmcnt(5) lgkmcnt(1)
	v_pk_fma_f32 v[56:57], v[50:51], v[6:7], v[62:63] op_sel_hi:[1,0,1]
	v_pk_fma_f32 v[58:59], v[48:49], v[6:7], v[72:73] op_sel_hi:[1,0,1]
	s_waitcnt vmcnt(4)
; #define LAS __attribute__((address_space(3)))
; #define LDS_WAIT() asm volatile("s_waitcnt lgkmcnt(0)" ::: "memory")
; #define DEC_LOADV(dst, i0) do { asm volatile("" ::: "memory"); _Pragma("unroll") for (int u = 0; u < 4; ++u) { const float* vr = cv + rbase + (size_t)((i0) + u) * 512; dst[u][0] = __builtin_nontemporal_load((const f32x4*)(vr + 4 * lane)); dst[u][1] = __builtin_nontemporal_load((const f32x4*)(vr + 256 + 4 * lane)); } } while (0)
; __device__ __forceinline__ void decode_item(Frame& F, const Args& a, int l, int item, unsigned char* ws) {
;     ...
;         DEC_LOADV(va, 0); DEC_LOADV(vb, 4); DEC_ACC(va, 0); DEC_LOADV(va, 8); DEC_ACC(vb, 4); DEC_LOADV(vb, 12); DEC_ACC(va, 8); DEC_LOADV(va, 16); DEC_ACC(vb, 12); DEC_LOADV(vb, 20); DEC_ACC(va, 16); DEC_LOADV(va, 24); DEC_ACC(vb, 20); DEC_LOADV(vb, 28); DEC_ACC(va, 24); DEC_ACC(vb, 28);
;     ...
;     }
;     __syncthreads();
;     LAS float* RED = (LAS float*)F.lds;
; #pragma unroll
;     for (int qi = 0; qi < 4; ++qi)
; #pragma unroll
;         for (int g = 0; g < 2; ++g) { LAS float* d = RED + ((w * 16 + qi * 4 + g * 2 + hh) * 128 + 4 * (lane & 31)); d[0] = O[qi][g][0]; d[1] = O[qi][g][1]; d[2] = O[qi][g][2]; d[3] = O[qi][g][3]; }
;     LDS_WAIT(); __syncthreads();
;     { f32x4 s = (f32x4){0.f, 0.f, 0.f, 0.f};
; #pragma unroll
;       for (int j = 0; j < 8; ++j) { const LAS float* p = RED + j * 2048 + tid * 4; s += (f32x4){p[0], p[1], p[2], p[3]}; }
;       *(f32x4*)((float*)(ws + WS_OSEG) + (size_t)(sb * 64 + seg) * 2048 + tid * 4) = s; }
;     __syncthreads();
	v_pk_fma_f32 v[62:63], v[42:43], v[6:7], v[74:75] op_sel:[0,1,0]
	v_pk_fma_f32 v[22:23], v[40:41], v[6:7], v[22:23] op_sel:[0,1,0]
	v_mov_b32_e32 v6, v9
	v_pk_fma_f32 v[64:65], v[42:43], v[6:7], v[68:69] op_sel_hi:[1,0,1]
	v_pk_fma_f32 v[24:25], v[40:41], v[6:7], v[24:25] op_sel_hi:[1,0,1]
	s_waitcnt lgkmcnt(0)
	v_mov_b32_e32 v6, v17
	v_pk_fma_f32 v[36:37], v[50:51], v[8:9], v[36:37] op_sel_hi:[1,0,1]
	v_pk_fma_f32 v[52:53], v[48:49], v[8:9], v[52:53] op_sel_hi:[1,0,1]
	v_pk_fma_f32 v[38:39], v[50:51], v[14:15], v[38:39] op_sel_hi:[1,0,1]
	v_pk_fma_f32 v[54:55], v[48:49], v[14:15], v[54:55] op_sel_hi:[1,0,1]
	v_pk_fma_f32 v[66:67], v[42:43], v[14:15], v[70:71] op_sel:[0,1,0]
	v_pk_fma_f32 v[30:31], v[40:41], v[14:15], v[30:31] op_sel:[0,1,0]
	v_pk_fma_f32 v[44:45], v[50:51], v[16:17], v[44:45] op_sel_hi:[1,0,1]
	v_pk_fma_f32 v[48:49], v[48:49], v[16:17], v[60:61] op_sel_hi:[1,0,1]
	v_pk_fma_f32 v[32:33], v[42:43], v[6:7], v[32:33] op_sel_hi:[1,0,1]
	v_pk_fma_f32 v[40:41], v[40:41], v[6:7], v[46:47] op_sel_hi:[1,0,1]
	ds_read_b128 v[6:9], v34 offset:18304
	ds_read_b128 v[14:17], v34 offset:18320
	s_waitcnt vmcnt(3) lgkmcnt(1)
	v_pk_fma_f32 v[42:43], v[28:29], v[6:7], v[56:57] op_sel_hi:[1,0,1]
	v_pk_fma_f32 v[46:47], v[26:27], v[6:7], v[58:59] op_sel_hi:[1,0,1]
	s_waitcnt vmcnt(2)
	v_pk_fma_f32 v[50:51], v[20:21], v[6:7], v[62:63] op_sel:[0,1,0]
	v_pk_fma_f32 v[22:23], v[18:19], v[6:7], v[22:23] op_sel:[0,1,0]
	v_mov_b32_e32 v6, v9
	v_pk_fma_f32 v[56:57], v[20:21], v[6:7], v[64:65] op_sel_hi:[1,0,1]
	v_pk_fma_f32 v[58:59], v[18:19], v[6:7], v[24:25] op_sel_hi:[1,0,1]
	s_waitcnt lgkmcnt(0)
	v_mov_b32_e32 v6, v17
	v_pk_fma_f32 v[36:37], v[28:29], v[8:9], v[36:37] op_sel_hi:[1,0,1]
	v_pk_fma_f32 v[52:53], v[26:27], v[8:9], v[52:53] op_sel_hi:[1,0,1]
	v_pk_fma_f32 v[38:39], v[28:29], v[14:15], v[38:39] op_sel_hi:[1,0,1]
	v_pk_fma_f32 v[54:55], v[26:27], v[14:15], v[54:55] op_sel_hi:[1,0,1]
	v_pk_fma_f32 v[60:61], v[20:21], v[14:15], v[66:67] op_sel:[0,1,0]
	v_pk_fma_f32 v[62:63], v[18:19], v[14:15], v[30:31] op_sel:[0,1,0]
	v_pk_fma_f32 v[44:45], v[28:29], v[16:17], v[44:45] op_sel_hi:[1,0,1]
	v_pk_fma_f32 v[48:49], v[26:27], v[16:17], v[48:49] op_sel_hi:[1,0,1]
	v_pk_fma_f32 v[64:65], v[20:21], v[6:7], v[32:33] op_sel_hi:[1,0,1]
	v_pk_fma_f32 v[40:41], v[18:19], v[6:7], v[40:41] op_sel_hi:[1,0,1]
	ds_read_b128 v[6:9], v34 offset:18368
	ds_read_b128 v[14:17], v34 offset:18384
	s_waitcnt lgkmcnt(0)
	s_barrier
	s_waitcnt vmcnt(1)
	v_pk_fma_f32 v[20:21], v[12:13], v[6:7], v[42:43] op_sel_hi:[1,0,1]
	v_pk_fma_f32 v[18:19], v[10:11], v[6:7], v[46:47] op_sel_hi:[1,0,1]
	s_waitcnt vmcnt(0)
	v_pk_fma_f32 v[24:25], v[4:5], v[6:7], v[50:51] op_sel:[0,1,0]
	v_pk_fma_f32 v[22:23], v[2:3], v[6:7], v[22:23] op_sel:[0,1,0]
	v_pk_fma_f32 v[28:29], v[12:13], v[8:9], v[36:37] op_sel_hi:[1,0,1]
	v_mov_b32_e32 v6, v9
	v_pk_fma_f32 v[32:33], v[12:13], v[14:15], v[38:39] op_sel_hi:[1,0,1]
	v_pk_fma_f32 v[30:31], v[10:11], v[14:15], v[54:55] op_sel_hi:[1,0,1]
	v_pk_fma_f32 v[38:39], v[4:5], v[14:15], v[60:61] op_sel:[0,1,0]
	v_pk_fma_f32 v[36:37], v[2:3], v[14:15], v[62:63] op_sel:[0,1,0]
	v_mov_b32_e32 v14, v17
	v_pk_fma_f32 v[26:27], v[10:11], v[8:9], v[52:53] op_sel_hi:[1,0,1]
	v_pk_fma_f32 v[8:9], v[4:5], v[6:7], v[56:57] op_sel_hi:[1,0,1]
	v_pk_fma_f32 v[6:7], v[2:3], v[6:7], v[58:59] op_sel_hi:[1,0,1]
	v_pk_fma_f32 v[4:5], v[4:5], v[14:15], v[64:65] op_sel_hi:[1,0,1]
	v_pk_fma_f32 v[2:3], v[2:3], v[14:15], v[40:41] op_sel_hi:[1,0,1]
	v_and_b32_e32 v14, 0x7c, v116
	v_pk_fma_f32 v[12:13], v[12:13], v[16:17], v[44:45] op_sel_hi:[1,0,1]
	v_pk_fma_f32 v[10:11], v[10:11], v[16:17], v[48:49] op_sel_hi:[1,0,1]
	v_lshl_add_u32 v14, v14, 2, 0
	v_lshlrev_b32_e64 v15, 13, s18
	v_lshlrev_b32_e32 v16, 9, v124
	v_add3_u32 v14, v14, v15, v16
	ds_write_b128 v14, v[18:21]
	ds_write_b128 v14, v[22:25] offset:1024
	ds_write_b128 v14, v[26:29] offset:2048
	ds_write_b128 v14, v[6:9] offset:3072
	ds_write_b128 v14, v[30:33] offset:4096
	ds_write_b128 v14, v[36:39] offset:5120
	ds_write_b128 v14, v[10:13] offset:6144
	ds_write_b128 v14, v[2:5] offset:7168
	v_lshl_add_u32 v10, v1, 4, 0
	s_waitcnt lgkmcnt(0)
	s_waitcnt lgkmcnt(0)
	s_barrier
	ds_read_b128 v[184:187], v10
	ds_read_b128 v[188:191], v10 offset:8192
	ds_read_b128 v[192:195], v10 offset:16384
	ds_read_b128 v[196:199], v10 offset:24576
	ds_read_b128 v[200:203], v10 offset:32768
	ds_read_b128 v[204:207], v10 offset:40960
	ds_read_b128 v[164:167], v10 offset:49152
	ds_read_b128 v[2:5], v10 offset:57344
	s_waitcnt lgkmcnt(7)
	v_pk_add_f32 v[6:7], v[186:187], 0 op_sel_hi:[1,0]
	v_pk_add_f32 v[8:9], v[184:185], 0 op_sel_hi:[1,0]
	s_waitcnt lgkmcnt(6)
	v_pk_add_f32 v[6:7], v[6:7], v[190:191]
	v_pk_add_f32 v[8:9], v[8:9], v[188:189]
	s_waitcnt lgkmcnt(5)
	v_pk_add_f32 v[6:7], v[6:7], v[194:195]
	v_pk_add_f32 v[8:9], v[8:9], v[192:193]
	s_waitcnt lgkmcnt(4)
	v_pk_add_f32 v[6:7], v[6:7], v[198:199]
	v_pk_add_f32 v[8:9], v[8:9], v[196:197]
	s_waitcnt lgkmcnt(3)
	v_pk_add_f32 v[6:7], v[6:7], v[202:203]
	v_pk_add_f32 v[8:9], v[8:9], v[200:201]
	s_waitcnt lgkmcnt(2)
	v_pk_add_f32 v[6:7], v[6:7], v[206:207]
	v_pk_add_f32 v[8:9], v[8:9], v[204:205]
	s_waitcnt lgkmcnt(1)
	v_pk_add_f32 v[6:7], v[6:7], v[166:167]
	v_pk_add_f32 v[8:9], v[8:9], v[164:165]
	s_waitcnt lgkmcnt(0)
	v_pk_add_f32 v[4:5], v[6:7], v[4:5]
	v_pk_add_f32 v[2:3], v[8:9], v[2:3]
	v_lshlrev_b64 v[6:7], 13, v[84:85]
	v_lshlrev_b32_e32 v8, 2, v1
	v_lshl_add_u64 v[6:7], s[10:11], 0, v[6:7]
	v_ashrrev_i32_e32 v9, 31, v8
	v_lshl_add_u64 v[6:7], v[8:9], 2, v[6:7]
	v_add_co_u32_e32 v6, vcc, 0x34700000, v6
	s_nop 1
	v_addc_co_u32_e32 v7, vcc, 0, v7, vcc
	global_store_dwordx4 v[6:7], v[2:5], off
	s_barrier
	s_cbranch_execnz .LBB0_1031
	s_branch .LBB0_1048
